# S5 scan units remapped so the workgroups of one XCD take neighbouring channel groups (shared 128-byte lines of u / y hit in that XCD's L2)
# speedup vs baseline: 1.0095x; 1.0029x over previous
; #define LAS __attribute__((address_space(3)))
; __device__ __forceinline__ void s5_phase(LAS unsigned char* lds, const bf16_t* USSM, const float* S5A, const float* S5B, const float* c_re, const float* c_im, const float* dskip,
;                                          bf16_t* YSSM, int tid, int lane, int wave) {
;     LAS float* carry = (LAS float*)lds;
;     LAS unsigned char* wb = lds + 4096 + wave * 13312;
;     LAS float* BU = (LAS float*)wb;
;     LAS bf16_t* XB = (LAS bf16_t*)(wb + 8448);
;     LAS bf16_t* UST = (LAS bf16_t*)(wb + 8448 + 4352);
;     const int r16 = lane & 15, q4 = lane >> 4;
;     const f32x4 z4 = {0.f, 0.f, 0.f, 0.f};
;     const bf16x8 zf = {0, 0, 0, 0, 0, 0, 0, 0};
;     for (int bg = blockIdx.x; bg < 256; bg += gridDim.x) {
;         const int b = bg >> 6, g = bg & 63;
;         __syncthreads();
;         const float are = S5A[(g * 64 + lane) * 2], aim = S5A[(g * 64 + lane) * 2 + 1];
;         bf16x8 bfr[8], cfr[4];
; #pragma unroll
;         for (int nt = 0; nt < 8; ++nt) { const int pp = nt * 16 + r16, p = pp & 63, im = pp >> 6; bfr[nt] = q4 < 2 ? pack_bf8(S5B + (size_t)(g * 64 + p) * 32 + im * 16 + q4 * 8, 1.f) : zf; }
; #pragma unroll
;         for (int ks = 0; ks < 4; ++ks) { const int pp = ks * 32 + q4 * 8, p = pp & 63, im = pp >> 6; cfr[ks] = pack_bf8((im ? c_im : c_re) + (size_t)(g * 16 + r16) * 64 + p, im ? -1.f : 1.f); }
;         const float dsk = dskip[g * 16 + r16];
;         const bf16_t* ub = USSM + ((size_t)(b * SEQ + wave * 1024)) * 1024 + g * 16;
.LBB0_566:
	s_cmpk_lt_i32 s2, 0x100
	v_readlane_b32 s90, v254, 17
	v_readlane_b32 s92, v254, 15
	s_cselect_b64 s[34:35], -1, 0
	s_cmpk_gt_i32 s2, 0xff
	v_readlane_b32 s91, v254, 18
	v_readlane_b32 s93, v254, 16
	s_cbranch_scc1 .LBB0_598
	s_ashr_i32 s6, s42, 6
	s_mul_i32 s0, s6, 0x3400
	v_and_b32_e32 v106, 63, v154
	s_lshl_b32 s8, s6, 9
	s_add_i32 s10, s0, 0
	v_and_b32_e32 v81, 15, v154
	s_add_i32 s8, s8, 0
	v_lshlrev_b32_e32 v5, 3, v106
	v_bfe_u32 v0, v154, 4, 2
	v_mov_b32_e32 v1, s10
	v_add_u32_e32 v107, s8, v5
	v_add_u32_e32 v108, 0, v5
	v_lshlrev_b32_e32 v5, 5, v81
	v_and_b32_e32 v6, 16, v154
	s_movk_i32 s11, 0x110
	v_lshlrev_b32_e32 v10, 2, v106
	s_lshl_b32 s3, s6, 10
	v_add3_u32 v109, s10, v5, v6
	v_mad_u32_u24 v5, v81, s11, v1
	v_lshl_or_b32 v1, v0, 6, v81
	v_bfe_u32 v8, v154, 2, 4
	v_and_b32_e32 v11, 12, v10
	s_cmp_gt_i32 s6, 0
	v_lshlrev_b32_e32 v9, 6, v8
	v_lshlrev_b32_e32 v12, 2, v11
	v_lshlrev_b32_e32 v112, 1, v1
	v_mov_b32_e32 v83, 0
	v_lshl_add_u32 v3, v81, 2, s10
	s_cselect_b64 s[8:9], -1, 0
	v_add3_u32 v110, s10, v9, v12
	v_lshlrev_b32_e32 v82, 1, v11
	v_readlane_b32 s62, v254, 21
	v_add_u32_e32 v111, s10, v10
	v_add_u32_e32 v113, s10, v112
	v_lshl_add_u32 v114, v1, 2, s10
	s_and_b32 s10, s6, 7
	v_lshl_add_u64 v[84:85], s[22:23], 0, v[82:83]
	v_lshlrev_b32_e32 v82, 5, v0
	v_readlane_b32 s63, v254, 22
	s_cmp_gt_u32 s6, 7
	v_lshlrev_b32_e32 v4, 1, v106
	v_lshl_add_u64 v[86:87], s[62:63], 0, v[82:83]
	s_cselect_b64 s[18:19], -1, 0
	s_and_b32 s11, s6, 0x7ffffff8
	v_lshl_add_u64 v[88:89], s[78:79], 0, v[82:83]
	v_lshl_add_u64 v[90:91], s[80:81], 0, v[82:83]
	v_lshl_or_b32 v82, v81, 11, v6
	v_lshlrev_b32_e32 v80, 3, v0
	v_lshlrev_b32_e32 v2, 6, v81
	v_and_b32_e32 v7, 48, v154
	v_mul_u32_u24_e32 v9, 0x840, v0
	v_sub_u32_e32 v4, 0, v4
	s_cmp_lg_u32 s10, 0
	v_lshl_add_u64 v[0:1], s[30:31], 0, v[82:83]
	s_mov_b64 s[14:15], 0x23900000
	s_mov_b32 s7, 0
	v_cmp_gt_u32_e64 s[0:1], 32, v106
	v_cmp_lt_u32_e64 s[4:5], 31, v106
	v_sub_u32_e32 v115, v114, v112
	s_cselect_b64 s[24:25], -1, 0
	v_lshl_add_u64 v[92:93], v[0:1], 0, s[14:15]
	s_lshl_b32 s27, s2, 7
	s_lshl_b32 s33, s84, 7
	v_or_b32_e32 v116, s3, v8
	s_mov_b64 s[52:53], 0x1000
	s_mov_b64 s[54:55], 0x1040
	v_lshlrev_b32_e32 v117, 2, v2
	s_mov_b64 s[56:57], 0x8000
	v_add_u32_e32 v118, v111, v4
	v_add_u32_e32 v119, v5, v7
	v_mov_b32_e32 v120, 0x800
	v_mov_b32_e32 v121, 0x1800
	v_add_u32_e32 v122, v3, v9
	s_and_b32 s43, s2, 7
	s_lshl_b32 s43, s43, 3
	s_bfe_u32 s42, s2, 0x30003
	s_or_b32 s43, s43, s42
	s_and_b32 s42, s2, 0xc0
	s_or_b32 s43, s43, s42
	s_cmpk_eq_u32 s84, 0x100
	s_cselect_b32 s43, s43, s2
	s_mov_b32 s42, s43
	s_lshl_b32 s27, s43, 7
